# skinny sample units (IN, PLE) start their operand loads without first draining the preceding stores; the in-order counted waits cover them
# speedup vs baseline: 1.0092x; 1.0092x over previous
; DI void gemm_ple(const Params& p, int bid, int nb, char* smem, const int tid) {
;     ...
;         const int m0 = tm * 256, n0 = tn * 128;
;         u32x2 gpk[4][4];
;         {
;             f32x4 gate[4][4]; zero_acc(gate);
;             gemm_stream2(XN, 1024, WG, 1024, 1024, m0, n0, true, PB, 256, WP, 256, m0, n0, smem, gate, tid, rg);
.Lpss_entry:
	s_waitcnt lgkmcnt(0)
	s_barrier
	v_readlane_b32 s55, v240, 0
	v_readlane_b32 s53, v238, 54
	v_readfirstlane_b32 s10, v193
	s_nop 3
	s_lshr_b32 s10, s10, 6
	s_cmpk_lt_u32 s55, 0x100
	s_cbranch_scc0 .Lple_exit
	v_and_b32_e32 v190, 63, v193
	v_and_b32_e32 v191, 15, v190
	v_lshrrev_b32_e32 v17, 4, v190
	v_lshlrev_b32_e32 v189, 4, v17
	s_and_b32 s3, s10, 3
	s_lshl_b32 s3, s3, 9
	v_lshl_add_u32 v187, v190, 3, s3
	v_add_u32_e32 v187, 16, v187

; DI void gemm_in(const Params& p, int l, int bid, int nb, char* smem, const int tid) {
;     ...
;     for (; have; tm = tm2, tn = tn2) {
;         have = ti.next(tm2, tn2);
;         const int m0 = tm * 256, n0 = tn * 128;
;         f32x4 acc[4][4]; zero_acc(acc);
;         gemm_stream(A, 1024, Bt, 1024, 1024, m0, n0, have, tm2 * 256, tn2 * 128, smem, acc, tid, rg);
.Lin_stub:
	v_readlane_b32 s55, v240, 0
	v_readlane_b32 s53, v238, 54
	v_readfirstlane_b32 s10, v193
	s_nop 3
	s_lshr_b32 s10, s10, 6
	s_cmpk_lt_u32 s55, 0x100
	s_cbranch_scc0 .LBB0_860
	v_and_b32_e32 v190, 63, v193
	v_and_b32_e32 v191, 15, v190
	v_lshrrev_b32_e32 v17, 4, v190
	v_lshlrev_b32_e32 v186, 4, v17
	v_lshl_add_u32 v186, v191, 11, v186
